# v79 + last-segment SSD blocks take 2 queued decode items before their own segment (fills the upstream-state wait)
# baseline (speedup 1.0000x reference)
; __global__ void __launch_bounds__(256, 2) mega(Params p) {
;     ...
;     for (int rep = 0; rep < REP_2B; ++rep) {
;       bool first = true;
;       for (;;) {
;         int it;
;         if (first) { it = (int)blockIdx.x; first = false; }
;         else it = next_item(ctr + layer * 2 + 1 + 8 * rep, &slot) + (int)gridDim.x;
;         if (rep > 0) { it += PROBE_2B_LO; if (it >= PROBE_2B_HI) break; }
;         if (it >= 288 + 192 + 24 + 256 + 1536) break;
;         it = (it < 192) ? (it + 384) : ((it < 480) ? (it - 192) : ((it < 504) ? (it + 608) : ((it < 760) ? (it + 328) : (it + 352))));
.Lmap2b_done:
	s_mov_b32 s98, 0
	v_writelane_b32 v255, s98, 52
	s_cmp_lt_u32 s2, 384
	s_cbranch_scc1 .Lst_go
	s_cmp_lt_u32 s2, 480
	s_cbranch_scc0 .Lst_go
	s_add_i32 s98, s2, 1
	v_writelane_b32 v255, s98, 52
	s_mov_b32 s98, 2
	v_writelane_b32 v255, s98, 53
	s_branch .LBB0_609

; __global__ void __launch_bounds__(256, 2) mega(Params p) {
;     ...
;         int it;
;         if (first) { it = (int)blockIdx.x; first = false; }
;         else it = next_item(ctr + layer * 2 + 1 + 8 * rep, &slot) + (int)gridDim.x;
;         if (rep > 0) { it += PROBE_2B_LO; if (it >= PROBE_2B_HI) break; }
;         if (it >= 288 + 192 + 24 + 256 + 1536) break;
.Lst_exitchk:
	v_readlane_b32 s98, v255, 52
	s_cmp_eq_u32 s98, 0
	s_cbranch_scc1 .LBB0_357
	s_add_i32 s2, s98, -1
	s_mov_b32 s98, 0
	v_writelane_b32 v255, s98, 52
	s_waitcnt vmcnt(0) lgkmcnt(0)
	s_branch .LBB0_358
	s_nop 0
	s_nop 0
	s_nop 0
	s_nop 0
	s_nop 0
	s_nop 0
	s_nop 0
	s_nop 0
	s_nop 0
	s_nop 0
	s_nop 0
	s_nop 0
	s_nop 0
	s_nop 0
	s_nop 0
	s_nop 0
	s_nop 0
	s_nop 0
	s_nop 0
	s_nop 0
	s_nop 0
	s_nop 0
	s_nop 0
	s_nop 0
	s_nop 0
	s_nop 0
	s_nop 0
	s_nop 0
	s_nop 0
	s_nop 0
	s_nop 0
	s_nop 0
	s_nop 0
	s_nop 0
	s_nop 0
	s_nop 0
	s_nop 0
	s_nop 0

; DI int next_item(unsigned* ctr, int* slot) {
;   __syncthreads();
;   if (threadIdx.x == 0) *slot = (int)atomicAdd(ctr, 1u);
;   __syncthreads();
;   return *slot;
; }
; __global__ void __launch_bounds__(256, 2) mega(Params p) {
;     ...
;         int it;
;         if (first) { it = (int)blockIdx.x; first = false; }
;         else it = next_item(ctr + layer * 2 + 1 + 8 * rep, &slot) + (int)gridDim.x;
.LBB0_609:
	s_setprio 0
	s_waitcnt lgkmcnt(0)
	s_barrier
	s_mov_b64 s[0:1], exec
	v_readlane_b32 s6, v252, 1
	v_readlane_b32 s7, v252, 2
	v_readlane_b32 s64, v255, 38
	s_and_b64 s[6:7], s[0:1], s[6:7]
	v_readlane_b32 s65, v255, 39
	s_xor_b64 s[0:1], s[6:7], s[0:1]
	v_readlane_b32 s65, v255, 40
	s_mov_b32 s66, 0x20000
	s_mov_b32 s67, 0x40000
	s_mov_b32 s68, 0x60000
	v_readlane_b32 s69, v255, 50
	s_mov_b32 s70, 0x3fd744fd
	v_readlane_b32 s98, v255, 52
	s_cmp_eq_u32 s98, 0
	s_cbranch_scc1 .Lst_none
	v_readlane_b32 s99, v255, 53
	s_cmp_eq_u32 s99, 0
	s_cbranch_scc1 .Lst_fire
	s_add_i32 s99, s99, -1
	v_writelane_b32 v255, s99, 53
	s_branch .Lst_none
.Lst_fire:
	s_add_i32 s2, s98, -1
	s_mov_b32 s98, 0
	v_writelane_b32 v255, s98, 52
	s_waitcnt vmcnt(0) lgkmcnt(0)
	s_mov_b64 s[0:1], 0
	s_branch .LBB0_357
	s_nop 0
	s_nop 0
	s_nop 0
	s_nop 0
	s_nop 0
	s_nop 0
	s_nop 0
	s_nop 0
	s_nop 0
	s_nop 0
	s_nop 0
	s_nop 0
	s_nop 0
	s_nop 0
	s_nop 0
	s_nop 0
	s_nop 0
	s_nop 0
	s_nop 0
	s_nop 0
	s_nop 0
	s_nop 0
	s_nop 0
	s_nop 0
	s_nop 0
	s_nop 0
	s_nop 0
	s_nop 0
	s_nop 0
	s_nop 0
	s_nop 0
	s_nop 0
	s_nop 0
	s_nop 0
	s_nop 0
	s_nop 0
	s_nop 0
	s_nop 0
	s_nop 0
	s_nop 0
	s_nop 0
	s_nop 0
	s_nop 0
	s_nop 0
	s_nop 0
.Lst_none:
	s_mov_b64 exec, s[6:7]
	s_cbranch_execz .LBB0_356
	s_mov_b64 s[8:9], exec
	s_waitcnt vmcnt(6)
	v_mbcnt_lo_u32_b32 v0, s8, 0
	v_mbcnt_hi_u32_b32 v0, s9, v0
	v_cmp_eq_u32_e32 vcc, 0, v0
	s_and_saveexec_b64 s[6:7], vcc
	s_cbranch_execz .LBB0_355
	s_bcnt1_i32_b64 s2, s[8:9]
	v_readlane_b32 s8, v255, 43
	v_mov_b32_e32 v1, s2
	v_readlane_b32 s9, v255, 44
	s_nop 4
	global_atomic_add v1, v161, v1, s[8:9] offset:4 sc0
	s_branch .LBB0_355
